# v39 + one static s_setprio 1 for the leading wave half (waves 0-3) during the VALU-bound Up and mixer-in epilogues, reset after the epilogue
# speedup vs baseline: 1.0060x; 1.0060x over previous
; #define PG8_BAR __builtin_amdgcn_s_barrier()
; template <class Epi, class Sched, bool ALIGN_EPI, bool SP2>
; __device__ __forceinline__ void gemm_phase(PG8_LAS unsigned char* lds, const Gemm g, const Sched& S, const Epi& E, int wid) {
;     ...
;         if (!has_next) break;
; #pragma unroll
;         for (int a = 0; a < 2; ++a)
; #pragma unroll
;             for (int b = 0; b < 2; ++b)
; #pragma unroll
;                 for (int m = 0; m < 4; ++m)
; #pragma unroll
;                     for (int n = 0; n < 2; ++n) acc[a][b][m][n] = (f32x4){0.f, 0.f, 0.f, 0.f};
;         cur = nxt; cA = nA; cB = nB; ++ui;
;         if constexpr (ALIGN_EPI) { if (wr == 1) PG8_BAR; }
.LBB0_369:
	s_setprio 0
	s_andn2_b64 vcc, exec, s[26:27]
	s_mov_b32 s70, s40
	s_mov_b32 s2, s22
	s_mov_b64 s[68:69], s[44:45]
	s_mov_b64 s[38:39], s[42:43]
	s_cbranch_vccz .LBB0_382

; #define PG8_BAR __builtin_amdgcn_s_barrier()
; #define LAS __attribute__((address_space(3)))
; template <class Epi, class Sched, bool ALIGN_EPI, bool SP2>
; __device__ __forceinline__ void gemm_phase(PG8_LAS unsigned char* lds, const Gemm g, const Sched& S, const Epi& E, int wid) {
;     ...
;         if constexpr (ALIGN_EPI) { if (wr == 0) PG8_BAR; }
; __device__ __forceinline__ void rows_rstd8_lds(const LAS unsigned char* xl, int lrow0, int fq, float (&rs)[8]) {
; #pragma unroll
;     for (int i = 0; i < 8; ++i) { const f32x4 p = *(const LAS f32x4*)(xl + (lrow0 + (i >> 2) * 128 + (i & 3) * 16) * 64 + 16 * fq);
;         float t = (p[0] + p[1]) + (p[2] + p[3]); t += __shfl_xor(t, 16); t += __shfl_xor(t, 32); rs[i] = rsqrtf(t * (1.0f / D) + EPS); }
.LBB0_377:
	s_and_b64 vcc, exec, s[20:21]
	s_cbranch_vccz .LBB0_379
	v_mbcnt_lo_u32_b32 v228, -1, 0
	v_mbcnt_hi_u32_b32 v228, -1, v228
	s_lshl_b32 s26, s15, 1
	v_add_u32_e32 v224, s26, v228
	v_lshlrev_b32_e32 v227, 2, v224
	v_lshlrev_b32_e32 v224, 6, v224
	v_add_u32_e32 v224, 0x22400, v224
	v_add_u32_e32 v227, 0x26800, v227
	ds_read_b128 v[216:219], v224
	ds_read_b128 v[220:223], v224 offset:16
	ds_read_b128 v[230:233], v224 offset:32
	ds_read_b128 v[242:245], v224 offset:48
	v_mov_b32_e32 v226, 0x358637bd
	s_waitcnt lgkmcnt(0)
	v_add_f32_e32 v216, v216, v217
	v_add_f32_e32 v218, v218, v219
	v_add_f32_e32 v220, v220, v221
	v_add_f32_e32 v222, v222, v223
	v_add_f32_e32 v230, v230, v231
	v_add_f32_e32 v232, v232, v233
	v_add_f32_e32 v242, v242, v243
	v_add_f32_e32 v244, v244, v245
	v_add_f32_e32 v216, v216, v218
	v_add_f32_e32 v220, v220, v222
	v_add_f32_e32 v230, v230, v232
	v_add_f32_e32 v242, v242, v244
	v_add_f32_e32 v216, v216, v220
	v_add_f32_e32 v230, v230, v242
	v_add_f32_e32 v225, v230, v216
	v_fma_f32 v225, v225, s16, v226
	v_rsq_f32_e32 v225, v225
	s_nop 0
	ds_write_b32 v227, v225
	s_waitcnt lgkmcnt(0)
	s_setprio 1
	s_barrier

; #define PG8_BAR __builtin_amdgcn_s_barrier()
; template <class Epi, class Sched, bool ALIGN_EPI, bool SP2>
; __device__ __forceinline__ void gemm_phase(PG8_LAS unsigned char* lds, const Gemm g, const Sched& S, const Epi& E, int wid) {
;     ...
;         if (!has_next) break;
; #pragma unroll
;         for (int a = 0; a < 2; ++a)
; #pragma unroll
;             for (int b = 0; b < 2; ++b)
; #pragma unroll
;                 for (int m = 0; m < 4; ++m)
; #pragma unroll
;                     for (int n = 0; n < 2; ++n) acc[a][b][m][n] = (f32x4){0.f, 0.f, 0.f, 0.f};
;         cur = nxt; cA = nA; cB = nB; ++ui;
;         if constexpr (ALIGN_EPI) { if (wr == 1) PG8_BAR; }
.LBB0_389:
	s_setprio 0
	s_andn2_b64 vcc, exec, s[22:23]
	s_mov_b32 s26, s68
	s_mov_b32 s2, s72
	s_mov_b64 s[40:41], s[78:79]
	s_mov_b64 s[38:39], s[74:75]
	s_cbranch_vccz .LBB0_482

; #define PG8_BAR __builtin_amdgcn_s_barrier()
; template <class Epi, class Sched, bool ALIGN_EPI, bool SP2>
; __device__ __forceinline__ void gemm_phase(PG8_LAS unsigned char* lds, const Gemm g, const Sched& S, const Epi& E, int wid) {
;     ...
;         if constexpr (ALIGN_EPI) { if (wr == 0) PG8_BAR; }
.LBB0_397:
	s_and_b64 vcc, exec, s[20:21]
	s_cbranch_vccz .LBB0_399
	s_setprio 1
	s_barrier
